# OWN attention combine: batched partial loads instead of one round trip per load; next-Q loads moved after combine
# speedup vs baseline: 1.0072x; 1.0072x over previous
.LBB0_64:
	s_and_b64 vcc, exec, s[10:11]
	s_cbranch_vccnz .Lown_noq
	v_lshl_add_u32 v16, s65, 8, v165
	v_ashrrev_i32_e32 v17, 31, v16
	v_lshlrev_b64 v[0:1], 8, v[16:17]
	v_or_b32_e32 v16, 16, v16
	s_lshl_b32 s8, s50, 22
	s_mov_b32 s9, s49
	v_ashrrev_i32_e32 v17, 31, v16
	v_lshl_add_u64 v[18:19], v[184:185], 0, s[8:9]
	v_lshlrev_b64 v[16:17], 8, v[16:17]
	v_lshl_add_u64 v[12:13], v[18:19], 0, v[0:1]
	v_lshl_add_u64 v[28:29], v[18:19], 0, v[16:17]
	global_load_dwordx4 v[0:3], v[12:13], off
	global_load_dwordx4 v[4:7], v[12:13], off offset:64
	global_load_dwordx4 v[8:11], v[12:13], off offset:128
	s_nop 0
	global_load_dwordx4 v[12:15], v[12:13], off offset:192
	s_nop 0
	global_load_dwordx4 v[16:19], v[28:29], off
	global_load_dwordx4 v[20:23], v[28:29], off offset:64
	global_load_dwordx4 v[24:27], v[28:29], off offset:128
	s_nop 0
	global_load_dwordx4 v[28:31], v[28:29], off offset:192

.LBB0_74:
	v_and_b32_e32 v149, 64, v197
	v_xor_b32_e32 v148, 16, v197
	v_add_u32_e32 v149, 64, v149
	v_cmp_lt_i32_e32 vcc, v148, v149
	s_min_i32 s58, s67, 3
	s_cmp_gt_i32 s67, 0
	v_cndmask_b32_e32 v148, v197, v148, vcc
	v_lshlrev_b32_e32 v152, 2, v148
	ds_bpermute_b32 v150, v152, v190
	v_xor_b32_e32 v148, 32, v197
	v_cmp_lt_i32_e32 vcc, v148, v149
	s_cselect_b64 s[24:25], -1, 0
	s_lshl_b64 s[8:9], s[48:49], 8
	v_cndmask_b32_e32 v148, v197, v148, vcc
	v_lshlrev_b32_e32 v153, 2, v148
	s_waitcnt lgkmcnt(0)
	v_add_f32_e32 v148, v190, v150
	ds_bpermute_b32 v149, v153, v148
	s_cmp_lt_i32 s67, 1
	s_mul_hi_u32 s59, s48, 12
	s_mul_i32 s62, s48, 12
	s_waitcnt lgkmcnt(0)
	v_add_f32_e32 v154, v148, v149
	s_cbranch_scc1 .LBB0_77
	s_add_u32 s68, s43, s62
	s_addc_u32 s69, s47, s59
	v_mov_b64_e32 v[148:149], s[68:69]
	s_movk_i32 s1, 0x60
	v_mad_i64_i32 v[148:149], s[68:69], v232, s1, v[148:149]
	v_mov_b64_e32 v[150:151], s[8:9]
	s_movk_i32 s1, 0x1800
	v_mad_i64_i32 v[150:151], s[68:69], v232, s1, v[150:151]
	v_lshl_add_u64 v[150:151], v[188:189], 0, v[150:151]
	global_load_dword v233, v[148:149], off
	global_load_dwordx2 v[0:1], v[150:151], off offset:-128
	global_load_dwordx2 v[2:3], v[150:151], off offset:-96
	global_load_dwordx2 v[4:5], v[150:151], off offset:-64
	global_load_dwordx2 v[6:7], v[150:151], off offset:-32
	global_load_dwordx2 v[8:9], v[150:151], off offset:0
	global_load_dwordx2 v[10:11], v[150:151], off offset:32
	global_load_dwordx2 v[12:13], v[150:151], off offset:64
	global_load_dwordx2 v[14:15], v[150:151], off offset:96
	s_cmp_lt_u32 s58, 2
	s_cbranch_scc1 .Lown_ld0_done
	global_load_dword v234, v[148:149], off offset:4
	global_load_dwordx2 v[16:17], v[150:151], off offset:1920
	global_load_dwordx2 v[18:19], v[150:151], off offset:1952
	global_load_dwordx2 v[20:21], v[150:151], off offset:1984
	global_load_dwordx2 v[22:23], v[150:151], off offset:2016
	global_load_dwordx2 v[24:25], v[150:151], off offset:2048
	global_load_dwordx2 v[26:27], v[150:151], off offset:2080
	global_load_dwordx2 v[28:29], v[150:151], off offset:2112
	global_load_dwordx2 v[30:31], v[150:151], off offset:2144
	s_cmp_lt_u32 s58, 3
	s_cbranch_scc1 .Lown_ld0_done
	global_load_dword v235, v[148:149], off offset:8
	v_add_co_u32_e32 v252, vcc, 0x1000, v150
	s_nop 1
	v_addc_co_u32_e32 v253, vcc, 0, v151, vcc
	global_load_dwordx2 v[236:237], v[252:253], off offset:-128
	global_load_dwordx2 v[238:239], v[252:253], off offset:-96
	global_load_dwordx2 v[240:241], v[252:253], off offset:-64
	global_load_dwordx2 v[242:243], v[252:253], off offset:-32
	global_load_dwordx2 v[244:245], v[252:253], off offset:0
	global_load_dwordx2 v[246:247], v[252:253], off offset:32
	global_load_dwordx2 v[248:249], v[252:253], off offset:64
	global_load_dwordx2 v[250:251], v[252:253], off offset:96
.Lown_ld0_done:
	v_add_co_u32_e32 v202, vcc, 0x600, v148
	s_nop 1
	v_addc_co_u32_e32 v203, vcc, 0, v149, vcc
	v_add_co_u32_e32 v204, vcc, 0x18000, v150
	s_nop 1
	v_addc_co_u32_e32 v205, vcc, 0, v151, vcc
	s_waitcnt vmcnt(0)
	v_add_f32_e32 v154, v154, v233
	v_lshlrev_b32_e32 v254, 16, v0
	v_and_b32_e32 v0, 0xffff0000, v0
	v_lshlrev_b32_e32 v155, 16, v1
	v_and_b32_e32 v1, 0xffff0000, v1
	v_add_f32_e32 v144, v144, v254
	v_add_f32_e32 v145, v145, v0
	v_add_f32_e32 v146, v146, v155
	v_add_f32_e32 v147, v147, v1
	v_lshlrev_b32_e32 v254, 16, v2
	v_and_b32_e32 v2, 0xffff0000, v2
	v_lshlrev_b32_e32 v155, 16, v3
	v_and_b32_e32 v3, 0xffff0000, v3
	v_add_f32_e32 v140, v140, v254
	v_add_f32_e32 v141, v141, v2
	v_add_f32_e32 v142, v142, v155
	v_add_f32_e32 v143, v143, v3
	v_lshlrev_b32_e32 v254, 16, v4
	v_and_b32_e32 v4, 0xffff0000, v4
	v_lshlrev_b32_e32 v155, 16, v5
	v_and_b32_e32 v5, 0xffff0000, v5
	v_add_f32_e32 v136, v136, v254
	v_add_f32_e32 v137, v137, v4
	v_add_f32_e32 v138, v138, v155
	v_add_f32_e32 v139, v139, v5
	v_lshlrev_b32_e32 v254, 16, v6
	v_and_b32_e32 v6, 0xffff0000, v6
	v_lshlrev_b32_e32 v155, 16, v7
	v_and_b32_e32 v7, 0xffff0000, v7
	v_add_f32_e32 v132, v132, v254
	v_add_f32_e32 v133, v133, v6
	v_add_f32_e32 v134, v134, v155
	v_add_f32_e32 v135, v135, v7
	v_lshlrev_b32_e32 v254, 16, v8
	v_and_b32_e32 v8, 0xffff0000, v8
	v_lshlrev_b32_e32 v155, 16, v9
	v_and_b32_e32 v9, 0xffff0000, v9
	v_add_f32_e32 v128, v128, v254
	v_add_f32_e32 v129, v129, v8
	v_add_f32_e32 v130, v130, v155
	v_add_f32_e32 v131, v131, v9
	v_lshlrev_b32_e32 v254, 16, v10
	v_and_b32_e32 v10, 0xffff0000, v10
	v_lshlrev_b32_e32 v155, 16, v11
	v_and_b32_e32 v11, 0xffff0000, v11
	v_add_f32_e32 v124, v124, v254
	v_add_f32_e32 v125, v125, v10
	v_add_f32_e32 v126, v126, v155
	v_add_f32_e32 v127, v127, v11
	v_lshlrev_b32_e32 v254, 16, v12
	v_and_b32_e32 v12, 0xffff0000, v12
	v_lshlrev_b32_e32 v155, 16, v13
	v_and_b32_e32 v13, 0xffff0000, v13
	v_add_f32_e32 v120, v120, v254
	v_add_f32_e32 v121, v121, v12
	v_add_f32_e32 v122, v122, v155
	v_add_f32_e32 v123, v123, v13
	v_lshlrev_b32_e32 v254, 16, v14
	v_and_b32_e32 v14, 0xffff0000, v14
	v_lshlrev_b32_e32 v155, 16, v15
	v_and_b32_e32 v15, 0xffff0000, v15
	v_add_f32_e32 v116, v116, v254
	v_add_f32_e32 v117, v117, v14
	v_add_f32_e32 v118, v118, v155
	v_add_f32_e32 v119, v119, v15
	s_cmp_lt_u32 s58, 2
	s_cbranch_scc1 .Lown_add0_done
	v_add_f32_e32 v154, v154, v234
	v_lshlrev_b32_e32 v254, 16, v16
	v_and_b32_e32 v16, 0xffff0000, v16
	v_lshlrev_b32_e32 v155, 16, v17
	v_and_b32_e32 v17, 0xffff0000, v17
	v_add_f32_e32 v144, v144, v254
	v_add_f32_e32 v145, v145, v16
	v_add_f32_e32 v146, v146, v155
	v_add_f32_e32 v147, v147, v17
	v_lshlrev_b32_e32 v254, 16, v18
	v_and_b32_e32 v18, 0xffff0000, v18
	v_lshlrev_b32_e32 v155, 16, v19
	v_and_b32_e32 v19, 0xffff0000, v19
	v_add_f32_e32 v140, v140, v254
	v_add_f32_e32 v141, v141, v18
	v_add_f32_e32 v142, v142, v155
	v_add_f32_e32 v143, v143, v19
	v_lshlrev_b32_e32 v254, 16, v20
	v_and_b32_e32 v20, 0xffff0000, v20
	v_lshlrev_b32_e32 v155, 16, v21
	v_and_b32_e32 v21, 0xffff0000, v21
	v_add_f32_e32 v136, v136, v254
	v_add_f32_e32 v137, v137, v20
	v_add_f32_e32 v138, v138, v155
	v_add_f32_e32 v139, v139, v21
	v_lshlrev_b32_e32 v254, 16, v22
	v_and_b32_e32 v22, 0xffff0000, v22
	v_lshlrev_b32_e32 v155, 16, v23
	v_and_b32_e32 v23, 0xffff0000, v23
	v_add_f32_e32 v132, v132, v254
	v_add_f32_e32 v133, v133, v22
	v_add_f32_e32 v134, v134, v155
	v_add_f32_e32 v135, v135, v23
	v_lshlrev_b32_e32 v254, 16, v24
	v_and_b32_e32 v24, 0xffff0000, v24
	v_lshlrev_b32_e32 v155, 16, v25
	v_and_b32_e32 v25, 0xffff0000, v25
	v_add_f32_e32 v128, v128, v254
	v_add_f32_e32 v129, v129, v24
	v_add_f32_e32 v130, v130, v155
	v_add_f32_e32 v131, v131, v25
	v_lshlrev_b32_e32 v254, 16, v26
	v_and_b32_e32 v26, 0xffff0000, v26
	v_lshlrev_b32_e32 v155, 16, v27
	v_and_b32_e32 v27, 0xffff0000, v27
	v_add_f32_e32 v124, v124, v254
	v_add_f32_e32 v125, v125, v26
	v_add_f32_e32 v126, v126, v155
	v_add_f32_e32 v127, v127, v27
	v_lshlrev_b32_e32 v254, 16, v28
	v_and_b32_e32 v28, 0xffff0000, v28
	v_lshlrev_b32_e32 v155, 16, v29
	v_and_b32_e32 v29, 0xffff0000, v29
	v_add_f32_e32 v120, v120, v254
	v_add_f32_e32 v121, v121, v28
	v_add_f32_e32 v122, v122, v155
	v_add_f32_e32 v123, v123, v29
	v_lshlrev_b32_e32 v254, 16, v30
	v_and_b32_e32 v30, 0xffff0000, v30
	v_lshlrev_b32_e32 v155, 16, v31
	v_and_b32_e32 v31, 0xffff0000, v31
	v_add_f32_e32 v116, v116, v254
	v_add_f32_e32 v117, v117, v30
	v_add_f32_e32 v118, v118, v155
	v_add_f32_e32 v119, v119, v31
	s_cmp_lt_u32 s58, 3
	s_cbranch_scc1 .Lown_add0_done
	v_add_f32_e32 v154, v154, v235
	v_lshlrev_b32_e32 v254, 16, v236
	v_and_b32_e32 v236, 0xffff0000, v236
	v_lshlrev_b32_e32 v155, 16, v237
	v_and_b32_e32 v237, 0xffff0000, v237
	v_add_f32_e32 v144, v144, v254
	v_add_f32_e32 v145, v145, v236
	v_add_f32_e32 v146, v146, v155
	v_add_f32_e32 v147, v147, v237
	v_lshlrev_b32_e32 v254, 16, v238
	v_and_b32_e32 v238, 0xffff0000, v238
	v_lshlrev_b32_e32 v155, 16, v239
	v_and_b32_e32 v239, 0xffff0000, v239
	v_add_f32_e32 v140, v140, v254
	v_add_f32_e32 v141, v141, v238
	v_add_f32_e32 v142, v142, v155
	v_add_f32_e32 v143, v143, v239
	v_lshlrev_b32_e32 v254, 16, v240
	v_and_b32_e32 v240, 0xffff0000, v240
	v_lshlrev_b32_e32 v155, 16, v241
	v_and_b32_e32 v241, 0xffff0000, v241
	v_add_f32_e32 v136, v136, v254
	v_add_f32_e32 v137, v137, v240
	v_add_f32_e32 v138, v138, v155
	v_add_f32_e32 v139, v139, v241
	v_lshlrev_b32_e32 v254, 16, v242
	v_and_b32_e32 v242, 0xffff0000, v242
	v_lshlrev_b32_e32 v155, 16, v243
	v_and_b32_e32 v243, 0xffff0000, v243
	v_add_f32_e32 v132, v132, v254
	v_add_f32_e32 v133, v133, v242
	v_add_f32_e32 v134, v134, v155
	v_add_f32_e32 v135, v135, v243
	v_lshlrev_b32_e32 v254, 16, v244
	v_and_b32_e32 v244, 0xffff0000, v244
	v_lshlrev_b32_e32 v155, 16, v245
	v_and_b32_e32 v245, 0xffff0000, v245
	v_add_f32_e32 v128, v128, v254
	v_add_f32_e32 v129, v129, v244
	v_add_f32_e32 v130, v130, v155
	v_add_f32_e32 v131, v131, v245
	v_lshlrev_b32_e32 v254, 16, v246
	v_and_b32_e32 v246, 0xffff0000, v246
	v_lshlrev_b32_e32 v155, 16, v247
	v_and_b32_e32 v247, 0xffff0000, v247
	v_add_f32_e32 v124, v124, v254
	v_add_f32_e32 v125, v125, v246
	v_add_f32_e32 v126, v126, v155
	v_add_f32_e32 v127, v127, v247
	v_lshlrev_b32_e32 v254, 16, v248
	v_and_b32_e32 v248, 0xffff0000, v248
	v_lshlrev_b32_e32 v155, 16, v249
	v_and_b32_e32 v249, 0xffff0000, v249
	v_add_f32_e32 v120, v120, v254
	v_add_f32_e32 v121, v121, v248
	v_add_f32_e32 v122, v122, v155
	v_add_f32_e32 v123, v123, v249
	v_lshlrev_b32_e32 v254, 16, v250
	v_and_b32_e32 v250, 0xffff0000, v250
	v_lshlrev_b32_e32 v155, 16, v251
	v_and_b32_e32 v251, 0xffff0000, v251
	v_add_f32_e32 v116, v116, v254
	v_add_f32_e32 v117, v117, v250
	v_add_f32_e32 v118, v118, v155
	v_add_f32_e32 v119, v119, v251
.Lown_add0_done:
	global_load_dword v233, v[202:203], off
	global_load_dwordx2 v[0:1], v[204:205], off offset:-128
	global_load_dwordx2 v[2:3], v[204:205], off offset:-96
	global_load_dwordx2 v[4:5], v[204:205], off offset:-64
	global_load_dwordx2 v[6:7], v[204:205], off offset:-32
	global_load_dwordx2 v[8:9], v[204:205], off offset:0
	global_load_dwordx2 v[10:11], v[204:205], off offset:32
	global_load_dwordx2 v[12:13], v[204:205], off offset:64
	global_load_dwordx2 v[14:15], v[204:205], off offset:96
	s_cmp_lt_u32 s58, 2
	s_cbranch_scc1 .Lown_ld1_done
	global_load_dword v234, v[202:203], off offset:4
	global_load_dwordx2 v[16:17], v[204:205], off offset:1920
	global_load_dwordx2 v[18:19], v[204:205], off offset:1952
	global_load_dwordx2 v[20:21], v[204:205], off offset:1984
	global_load_dwordx2 v[22:23], v[204:205], off offset:2016
	global_load_dwordx2 v[24:25], v[204:205], off offset:2048
	global_load_dwordx2 v[26:27], v[204:205], off offset:2080
	global_load_dwordx2 v[28:29], v[204:205], off offset:2112
	global_load_dwordx2 v[30:31], v[204:205], off offset:2144
	s_cmp_lt_u32 s58, 3
	s_cbranch_scc1 .Lown_ld1_done
	global_load_dword v235, v[202:203], off offset:8
	v_add_co_u32_e32 v252, vcc, 0x1000, v204
	s_nop 1
	v_addc_co_u32_e32 v253, vcc, 0, v205, vcc
	global_load_dwordx2 v[236:237], v[252:253], off offset:-128
	global_load_dwordx2 v[238:239], v[252:253], off offset:-96
	global_load_dwordx2 v[240:241], v[252:253], off offset:-64
	global_load_dwordx2 v[242:243], v[252:253], off offset:-32
	global_load_dwordx2 v[244:245], v[252:253], off offset:0
	global_load_dwordx2 v[246:247], v[252:253], off offset:32
	global_load_dwordx2 v[248:249], v[252:253], off offset:64
	global_load_dwordx2 v[250:251], v[252:253], off offset:96
.Lown_ld1_done:
.LBB0_77:
	v_div_scale_f32 v148, s[68:69], v154, v154, 1.0
	v_rcp_f32_e32 v149, v148
	v_div_scale_f32 v150, vcc, 1.0, v154, 1.0
	v_fma_f32 v151, -v148, v149, 1.0
	v_fmac_f32_e32 v149, v151, v149
	v_mul_f32_e32 v151, v150, v149
	v_fma_f32 v155, -v148, v151, v150
	v_fmac_f32_e32 v151, v155, v149
	v_fma_f32 v148, -v148, v151, v150
	v_div_fmas_f32 v148, v148, v149, v151
	v_div_fixup_f32 v150, v148, v154, 1.0
	v_mad_i64_i32 v[148:149], s[68:69], v232, 24, 0
	v_or_b32_e32 v148, s48, v148
	v_lshlrev_b64 v[148:149], 8, v[148:149]
	v_mul_f32_e32 v144, v144, v150
	v_mul_f32_e32 v145, v145, v150
	v_lshl_add_u64 v[148:149], v[186:187], 0, v[148:149]
	v_cvt_pk_bf16_f32 v144, v144, v145
	v_mul_f32_e32 v145, v146, v150
	v_mul_f32_e32 v140, v140, v150
	v_mul_f32_e32 v141, v141, v150
	v_mul_f32_e32 v146, v147, v150
	v_cvt_pk_bf16_f32 v145, v145, v146
	global_store_dwordx2 v[148:149], v[144:145], off
	v_cvt_pk_bf16_f32 v140, v140, v141
	v_mul_f32_e32 v141, v142, v150
	v_mul_f32_e32 v136, v136, v150
	v_mul_f32_e32 v137, v137, v150
	v_mul_f32_e32 v142, v143, v150
	v_cvt_pk_bf16_f32 v141, v141, v142
	global_store_dwordx2 v[148:149], v[140:141], off offset:32
	v_cvt_pk_bf16_f32 v136, v136, v137
	v_mul_f32_e32 v137, v138, v150
	v_mul_f32_e32 v132, v132, v150
	v_mul_f32_e32 v133, v133, v150
	v_mul_f32_e32 v138, v139, v150
	v_cvt_pk_bf16_f32 v137, v137, v138
	global_store_dwordx2 v[148:149], v[136:137], off offset:64
	v_cvt_pk_bf16_f32 v132, v132, v133
	v_mul_f32_e32 v133, v134, v150
	v_mul_f32_e32 v128, v128, v150
	v_mul_f32_e32 v129, v129, v150
	v_mul_f32_e32 v134, v135, v150
	v_cvt_pk_bf16_f32 v133, v133, v134
	global_store_dwordx2 v[148:149], v[132:133], off offset:96
	v_cvt_pk_bf16_f32 v128, v128, v129
	v_mul_f32_e32 v129, v130, v150
	v_mul_f32_e32 v124, v124, v150
	v_mul_f32_e32 v125, v125, v150
	v_mul_f32_e32 v130, v131, v150
	v_cvt_pk_bf16_f32 v129, v129, v130
	global_store_dwordx2 v[148:149], v[128:129], off offset:128
	v_cvt_pk_bf16_f32 v124, v124, v125
	v_mul_f32_e32 v125, v126, v150
	v_mul_f32_e32 v120, v120, v150
	v_mul_f32_e32 v121, v121, v150
	v_mul_f32_e32 v126, v127, v150
	v_cvt_pk_bf16_f32 v125, v125, v126
	global_store_dwordx2 v[148:149], v[124:125], off offset:160
	v_cvt_pk_bf16_f32 v120, v120, v121
	v_mul_f32_e32 v121, v122, v150
	v_mul_f32_e32 v122, v123, v150
	v_cvt_pk_bf16_f32 v121, v121, v122
	ds_bpermute_b32 v122, v152, v191
	global_store_dwordx2 v[148:149], v[120:121], off offset:192
	v_mul_f32_e32 v116, v116, v150
	v_mul_f32_e32 v117, v117, v150
	v_cvt_pk_bf16_f32 v116, v116, v117
	s_waitcnt lgkmcnt(0)
	v_add_f32_e32 v120, v191, v122
	ds_bpermute_b32 v121, v153, v120
	v_mul_f32_e32 v117, v118, v150
	s_and_b64 vcc, exec, s[24:25]
	v_mul_f32_e32 v118, v119, v150
	v_cvt_pk_bf16_f32 v117, v117, v118
	s_waitcnt lgkmcnt(0)
	v_add_f32_e32 v120, v120, v121
	global_store_dwordx2 v[148:149], v[116:117], off offset:224
	s_cbranch_vccz .LBB0_64
	s_waitcnt vmcnt(8)
	v_add_f32_e32 v120, v120, v233
	v_lshlrev_b32_e32 v254, 16, v0
	v_and_b32_e32 v0, 0xffff0000, v0
	v_lshlrev_b32_e32 v155, 16, v1
	v_and_b32_e32 v1, 0xffff0000, v1
	v_add_f32_e32 v112, v112, v254
	v_add_f32_e32 v113, v113, v0
	v_add_f32_e32 v114, v114, v155
	v_add_f32_e32 v115, v115, v1
	v_lshlrev_b32_e32 v254, 16, v2
	v_and_b32_e32 v2, 0xffff0000, v2
	v_lshlrev_b32_e32 v155, 16, v3
	v_and_b32_e32 v3, 0xffff0000, v3
	v_add_f32_e32 v108, v108, v254
	v_add_f32_e32 v109, v109, v2
	v_add_f32_e32 v110, v110, v155
	v_add_f32_e32 v111, v111, v3
	v_lshlrev_b32_e32 v254, 16, v4
	v_and_b32_e32 v4, 0xffff0000, v4
	v_lshlrev_b32_e32 v155, 16, v5
	v_and_b32_e32 v5, 0xffff0000, v5
	v_add_f32_e32 v104, v104, v254
	v_add_f32_e32 v105, v105, v4
	v_add_f32_e32 v106, v106, v155
	v_add_f32_e32 v107, v107, v5
	v_lshlrev_b32_e32 v254, 16, v6
	v_and_b32_e32 v6, 0xffff0000, v6
	v_lshlrev_b32_e32 v155, 16, v7
	v_and_b32_e32 v7, 0xffff0000, v7
	v_add_f32_e32 v100, v100, v254
	v_add_f32_e32 v101, v101, v6
	v_add_f32_e32 v102, v102, v155
	v_add_f32_e32 v103, v103, v7
	v_lshlrev_b32_e32 v254, 16, v8
	v_and_b32_e32 v8, 0xffff0000, v8
	v_lshlrev_b32_e32 v155, 16, v9
	v_and_b32_e32 v9, 0xffff0000, v9
	v_add_f32_e32 v96, v96, v254
	v_add_f32_e32 v97, v97, v8
	v_add_f32_e32 v98, v98, v155
	v_add_f32_e32 v99, v99, v9
	v_lshlrev_b32_e32 v254, 16, v10
	v_and_b32_e32 v10, 0xffff0000, v10
	v_lshlrev_b32_e32 v155, 16, v11
	v_and_b32_e32 v11, 0xffff0000, v11
	v_add_f32_e32 v92, v92, v254
	v_add_f32_e32 v93, v93, v10
	v_add_f32_e32 v94, v94, v155
	v_add_f32_e32 v95, v95, v11
	v_lshlrev_b32_e32 v254, 16, v12
	v_and_b32_e32 v12, 0xffff0000, v12
	v_lshlrev_b32_e32 v155, 16, v13
	v_and_b32_e32 v13, 0xffff0000, v13
	v_add_f32_e32 v88, v88, v254
	v_add_f32_e32 v89, v89, v12
	v_add_f32_e32 v90, v90, v155
	v_add_f32_e32 v91, v91, v13
	v_lshlrev_b32_e32 v254, 16, v14
	v_and_b32_e32 v14, 0xffff0000, v14
	v_lshlrev_b32_e32 v155, 16, v15
	v_and_b32_e32 v15, 0xffff0000, v15
	v_add_f32_e32 v84, v84, v254
	v_add_f32_e32 v85, v85, v14
	v_add_f32_e32 v86, v86, v155
	v_add_f32_e32 v87, v87, v15
	s_cmp_lt_u32 s58, 2
	s_cbranch_scc1 .Lown_add1_done
	v_add_f32_e32 v120, v120, v234
	v_lshlrev_b32_e32 v254, 16, v16
	v_and_b32_e32 v16, 0xffff0000, v16
	v_lshlrev_b32_e32 v155, 16, v17
	v_and_b32_e32 v17, 0xffff0000, v17
	v_add_f32_e32 v112, v112, v254
	v_add_f32_e32 v113, v113, v16
	v_add_f32_e32 v114, v114, v155
	v_add_f32_e32 v115, v115, v17
	v_lshlrev_b32_e32 v254, 16, v18
	v_and_b32_e32 v18, 0xffff0000, v18
	v_lshlrev_b32_e32 v155, 16, v19
	v_and_b32_e32 v19, 0xffff0000, v19
	v_add_f32_e32 v108, v108, v254
	v_add_f32_e32 v109, v109, v18
	v_add_f32_e32 v110, v110, v155
	v_add_f32_e32 v111, v111, v19
	v_lshlrev_b32_e32 v254, 16, v20
	v_and_b32_e32 v20, 0xffff0000, v20
	v_lshlrev_b32_e32 v155, 16, v21
	v_and_b32_e32 v21, 0xffff0000, v21
	v_add_f32_e32 v104, v104, v254
	v_add_f32_e32 v105, v105, v20
	v_add_f32_e32 v106, v106, v155
	v_add_f32_e32 v107, v107, v21
	v_lshlrev_b32_e32 v254, 16, v22
	v_and_b32_e32 v22, 0xffff0000, v22
	v_lshlrev_b32_e32 v155, 16, v23
	v_and_b32_e32 v23, 0xffff0000, v23
	v_add_f32_e32 v100, v100, v254
	v_add_f32_e32 v101, v101, v22
	v_add_f32_e32 v102, v102, v155
	v_add_f32_e32 v103, v103, v23
	v_lshlrev_b32_e32 v254, 16, v24
	v_and_b32_e32 v24, 0xffff0000, v24
	v_lshlrev_b32_e32 v155, 16, v25
	v_and_b32_e32 v25, 0xffff0000, v25
	v_add_f32_e32 v96, v96, v254
	v_add_f32_e32 v97, v97, v24
	v_add_f32_e32 v98, v98, v155
	v_add_f32_e32 v99, v99, v25
	v_lshlrev_b32_e32 v254, 16, v26
	v_and_b32_e32 v26, 0xffff0000, v26
	v_lshlrev_b32_e32 v155, 16, v27
	v_and_b32_e32 v27, 0xffff0000, v27
	v_add_f32_e32 v92, v92, v254
	v_add_f32_e32 v93, v93, v26
	v_add_f32_e32 v94, v94, v155
	v_add_f32_e32 v95, v95, v27
	v_lshlrev_b32_e32 v254, 16, v28
	v_and_b32_e32 v28, 0xffff0000, v28
	v_lshlrev_b32_e32 v155, 16, v29
	v_and_b32_e32 v29, 0xffff0000, v29
	v_add_f32_e32 v88, v88, v254
	v_add_f32_e32 v89, v89, v28
	v_add_f32_e32 v90, v90, v155
	v_add_f32_e32 v91, v91, v29
	v_lshlrev_b32_e32 v254, 16, v30
	v_and_b32_e32 v30, 0xffff0000, v30
	v_lshlrev_b32_e32 v155, 16, v31
	v_and_b32_e32 v31, 0xffff0000, v31
	v_add_f32_e32 v84, v84, v254
	v_add_f32_e32 v85, v85, v30
	v_add_f32_e32 v86, v86, v155
	v_add_f32_e32 v87, v87, v31
	s_cmp_lt_u32 s58, 3
	s_cbranch_scc1 .Lown_add1_done
	v_add_f32_e32 v120, v120, v235
	v_lshlrev_b32_e32 v254, 16, v236
	v_and_b32_e32 v236, 0xffff0000, v236
	v_lshlrev_b32_e32 v155, 16, v237
	v_and_b32_e32 v237, 0xffff0000, v237
	v_add_f32_e32 v112, v112, v254
	v_add_f32_e32 v113, v113, v236
	v_add_f32_e32 v114, v114, v155
	v_add_f32_e32 v115, v115, v237
	v_lshlrev_b32_e32 v254, 16, v238
	v_and_b32_e32 v238, 0xffff0000, v238
	v_lshlrev_b32_e32 v155, 16, v239
	v_and_b32_e32 v239, 0xffff0000, v239
	v_add_f32_e32 v108, v108, v254
	v_add_f32_e32 v109, v109, v238
	v_add_f32_e32 v110, v110, v155
	v_add_f32_e32 v111, v111, v239
	v_lshlrev_b32_e32 v254, 16, v240
	v_and_b32_e32 v240, 0xffff0000, v240
	v_lshlrev_b32_e32 v155, 16, v241
	v_and_b32_e32 v241, 0xffff0000, v241
	v_add_f32_e32 v104, v104, v254
	v_add_f32_e32 v105, v105, v240
	v_add_f32_e32 v106, v106, v155
	v_add_f32_e32 v107, v107, v241
	v_lshlrev_b32_e32 v254, 16, v242
	v_and_b32_e32 v242, 0xffff0000, v242
	v_lshlrev_b32_e32 v155, 16, v243
	v_and_b32_e32 v243, 0xffff0000, v243
	v_add_f32_e32 v100, v100, v254
	v_add_f32_e32 v101, v101, v242
	v_add_f32_e32 v102, v102, v155
	v_add_f32_e32 v103, v103, v243
	v_lshlrev_b32_e32 v254, 16, v244
	v_and_b32_e32 v244, 0xffff0000, v244
	v_lshlrev_b32_e32 v155, 16, v245
	v_and_b32_e32 v245, 0xffff0000, v245
	v_add_f32_e32 v96, v96, v254
	v_add_f32_e32 v97, v97, v244
	v_add_f32_e32 v98, v98, v155
	v_add_f32_e32 v99, v99, v245
	v_lshlrev_b32_e32 v254, 16, v246
	v_and_b32_e32 v246, 0xffff0000, v246
	v_lshlrev_b32_e32 v155, 16, v247
	v_and_b32_e32 v247, 0xffff0000, v247
	v_add_f32_e32 v92, v92, v254
	v_add_f32_e32 v93, v93, v246
	v_add_f32_e32 v94, v94, v155
	v_add_f32_e32 v95, v95, v247
	v_lshlrev_b32_e32 v254, 16, v248
	v_and_b32_e32 v248, 0xffff0000, v248
	v_lshlrev_b32_e32 v155, 16, v249
	v_and_b32_e32 v249, 0xffff0000, v249
	v_add_f32_e32 v88, v88, v254
	v_add_f32_e32 v89, v89, v248
	v_add_f32_e32 v90, v90, v155
	v_add_f32_e32 v91, v91, v249
	v_lshlrev_b32_e32 v254, 16, v250
	v_and_b32_e32 v250, 0xffff0000, v250
	v_lshlrev_b32_e32 v155, 16, v251
	v_and_b32_e32 v251, 0xffff0000, v251
	v_add_f32_e32 v84, v84, v254
	v_add_f32_e32 v85, v85, v250
	v_add_f32_e32 v86, v86, v155
	v_add_f32_e32 v87, v87, v251
.Lown_add1_done:
	s_branch .LBB0_64
.LBB0_80:
	s_and_b64 vcc, exec, s[6:7]
	s_cbranch_vccnz .LBB0_505
	s_branch .LBB0_579
